# conv_fix_rows: issue the Z[t-1]/Z[t-2] loads without intermediate waits (one round trip per fix-up row instead of three)
# baseline (speedup 1.0000x reference)
.LBB0_239:
	s_ashr_i32 s4, s16, 3
	s_add_i32 s4, s23, s4
	s_ashr_i32 s5, s4, 31
	s_lshr_b32 s5, s5, 27
	s_add_i32 s5, s4, s5
	s_ashr_i32 s10, s5, 5
	s_lshl_b32 s10, s10, 3
	s_sub_i32 s11, 0x80, s10
	s_min_i32 s11, s11, 8
	s_abs_i32 s11, s11
	v_cvt_f32_u32_e32 v24, s11
	s_sub_i32 s16, 0, s11
	s_andn2_b32 s5, s5, 31
	s_sub_i32 s4, s4, s5
	v_rcp_iflag_f32_e32 v24, v24
	s_ashr_i32 s5, s4, 31
	s_abs_i32 s4, s4
	v_mov_b32_e32 v40, 0
	v_mul_f32_e32 v24, 0x4f7ffffe, v24
	v_cvt_u32_f32_e32 v24, v24
	v_mov_b32_e32 v38, 0
	v_mov_b32_e32 v39, 0
	v_mov_b32_e32 v42, 0
	v_readfirstlane_b32 s22, v24
	s_mul_i32 s16, s16, s22
	s_mul_hi_u32 s16, s22, s16
	s_add_i32 s22, s22, s16
	s_mul_hi_u32 s16, s4, s22
	s_mul_i32 s16, s16, s11
	s_sub_i32 s4, s4, s16
	s_sub_i32 s16, s4, s11
	s_cmp_ge_u32 s4, s11
	s_cselect_b32 s4, s16, s4
	s_sub_i32 s16, s4, s11
	s_cmp_ge_u32 s4, s11
	s_cselect_b32 s4, s16, s4
	s_xor_b32 s4, s4, s5
	s_sub_i32 s4, s4, s5
	s_add_i32 s10, s10, s4
	v_lshl_add_u32 v36, s10, 8, v33
	v_ashrrev_i32_e32 v37, 31, v36
	v_lshlrev_b64 v[34:35], 10, v[36:37]
	v_or_b32_e32 v34, v34, v32
	v_lshlrev_b64 v[24:25], 1, v[34:35]
	v_lshl_add_u64 v[48:49], s[12:13], 0, v[24:25]
	v_lshl_add_u64 v[24:25], s[18:19], 0, v[24:25]
	global_load_dwordx4 v[28:31], v[48:49], off
	s_nop 0
	global_load_dwordx4 v[24:27], v[24:25], off
	v_and_b32_e32 v41, 0x7ff, v36
	v_cmp_ne_u32_e32 vcc, 0, v41
	v_mov_b32_e32 v128, 0
	v_mov_b32_e32 v129, 0
	v_mov_b32_e32 v130, 0
	v_mov_b32_e32 v131, 0
	v_mov_b32_e32 v132, 0
	v_mov_b32_e32 v133, 0
	v_mov_b32_e32 v134, 0
	v_mov_b32_e32 v135, 0
	s_and_saveexec_b64 s[10:11], vcc
	global_load_dwordx4 v[128:131], v[48:49], off offset:-2048
	s_or_b64 exec, exec, s[10:11]
	v_cmp_lt_u32_e32 vcc, 1, v41
	s_and_saveexec_b64 s[10:11], vcc
	global_load_dwordx4 v[132:135], v[48:49], off offset:-4096
	s_or_b64 exec, exec, s[10:11]
	s_waitcnt vmcnt(0)
	v_lshlrev_b32_e32 v42, 16, v128
	v_and_b32_e32 v43, 0xffff0000, v128
	v_lshlrev_b32_e32 v44, 16, v129
	v_and_b32_e32 v45, 0xffff0000, v129
	v_lshlrev_b32_e32 v36, 16, v130
	v_and_b32_e32 v37, 0xffff0000, v130
	v_lshlrev_b32_e32 v38, 16, v131
	v_and_b32_e32 v39, 0xffff0000, v131
	v_lshlrev_b32_e32 v50, 16, v132
	v_and_b32_e32 v51, 0xffff0000, v132
	v_lshlrev_b32_e32 v52, 16, v133
	v_and_b32_e32 v53, 0xffff0000, v133
	v_lshlrev_b32_e32 v40, 16, v134
	v_and_b32_e32 v41, 0xffff0000, v134
	v_lshlrev_b32_e32 v46, 16, v135
	v_and_b32_e32 v47, 0xffff0000, v135
	s_branch .LBB0_232
